# sample-unit compressed branch loads 4 in flight, table unchanged (222/286)
# speedup vs baseline: 1.0174x; 1.0007x over previous
.LBB0_1408:
	s_or_b64 exec, exec, s[2:3]
	v_ashrrev_i32_e32 v1, 6, v145
	v_bfe_u32 v105, v145, 4, 2
	v_lshlrev_b32_e32 v223, 2, v1
	s_lshl_b32 s16, s95, 9
	s_lshl_b32 s8, s96, 7
	v_and_b32_e32 v147, 15, v145
	v_or_b32_e32 v121, v223, v105
	s_add_u32 s0, s86, s8
	s_addc_u32 s1, s87, 0
	v_lshlrev_b32_e32 v2, 3, v147
	v_add_u32_e32 v52, s16, v121
	v_lshl_add_u64 v[20:21], s[0:1], 0, v[2:3]
	v_cmp_gt_i32_e64 s[56:57], s14, v121
	v_mov_b32_e32 v45, 0
	v_ashrrev_i32_e32 v53, 31, v52
	v_mov_b32_e32 v49, 0
	v_mov_b32_e32 v51, 0
	v_mov_b32_e32 v50, 0
	s_waitcnt vmcnt(0)
	v_mov_b32_e32 v68, 0
	s_waitcnt lgkmcnt(0)
	s_barrier
	v_mov_b32_e32 v202, 0
	v_mov_b32_e32 v203, 0
	s_and_saveexec_b64 s[2:3], s[56:57]
	s_cbranch_execz .LBB0_1410
	v_lshlrev_b64 v[202:203], 9, v[52:53]
	v_lshl_add_u64 v[202:203], v[20:21], 0, v[202:203]
	global_load_dwordx2 v[202:203], v[202:203], off
.LBB0_1410:
	s_or_b64 exec, exec, s[2:3]
	v_add_u32_e32 v123, 32, v121
	s_movk_i32 s0, 0x1df
	v_add_u32_e32 v54, s16, v123
	v_cmp_gt_i32_e64 s[54:55], s0, v121
	v_ashrrev_i32_e32 v55, 31, v54
	v_mov_b32_e32 v47, 0
	v_mov_b32_e32 v46, 0
	v_mov_b32_e32 v48, 0
	v_mov_b32_e32 v248, 0
	v_mov_b32_e32 v249, 0
	s_and_saveexec_b64 s[2:3], s[54:55]
	s_cbranch_execz .LBB0_1412
	v_lshlrev_b64 v[248:249], 9, v[54:55]
	v_lshl_add_u64 v[248:249], v[20:21], 0, v[248:249]
	global_load_dwordx2 v[248:249], v[248:249], off
.LBB0_1412:
	s_or_b64 exec, exec, s[2:3]
	v_add_u32_e32 v119, 64, v121
	s_movk_i32 s0, 0x1bf
	v_add_u32_e32 v56, s16, v119
	v_cmp_gt_i32_e64 s[52:53], s0, v121
	v_mov_b32_e32 v37, 0
	v_ashrrev_i32_e32 v57, 31, v56
	v_mov_b32_e32 v41, 0
	v_mov_b32_e32 v43, 0
	v_mov_b32_e32 v42, 0
	v_mov_b32_e32 v44, 0
	v_mov_b32_e32 v250, 0
	v_mov_b32_e32 v251, 0
	s_and_saveexec_b64 s[2:3], s[52:53]
	s_cbranch_execz .LBB0_1414
	v_lshlrev_b64 v[250:251], 9, v[56:57]
	v_lshl_add_u64 v[250:251], v[20:21], 0, v[250:251]
	global_load_dwordx2 v[250:251], v[250:251], off

.LBB0_1416:
	s_or_b64 exec, exec, s[2:3]
	s_waitcnt vmcnt(0)
	v_lshlrev_b32_e32 v49, 16, v202
	v_and_b32_e32 v51, 0xffff0000, v202
	v_lshlrev_b32_e32 v50, 16, v203
	v_and_b32_e32 v68, 0xffff0000, v203
	v_lshlrev_b32_e32 v45, 16, v248
	v_and_b32_e32 v47, 0xffff0000, v248
	v_lshlrev_b32_e32 v46, 16, v249
	v_and_b32_e32 v48, 0xffff0000, v249
	v_lshlrev_b32_e32 v41, 16, v250
	v_and_b32_e32 v43, 0xffff0000, v250
	v_lshlrev_b32_e32 v42, 16, v251
	v_and_b32_e32 v44, 0xffff0000, v251
	v_add_u32_e32 v115, 0x80, v121
	s_movk_i32 s0, 0x17f
	v_add_u32_e32 v60, s16, v115
	v_cmp_gt_i32_e64 s[46:47], s0, v121
	v_mov_b32_e32 v29, 0
	v_ashrrev_i32_e32 v61, 31, v60
	v_mov_b32_e32 v33, 0
	v_mov_b32_e32 v35, 0
	v_mov_b32_e32 v34, 0
	v_mov_b32_e32 v36, 0
	v_mov_b32_e32 v202, 0
	v_mov_b32_e32 v203, 0
	s_and_saveexec_b64 s[2:3], s[46:47]
	s_cbranch_execz .LBB0_1418
	v_lshlrev_b64 v[202:203], 9, v[60:61]
	v_lshl_add_u64 v[202:203], v[20:21], 0, v[202:203]
	global_load_dwordx2 v[202:203], v[202:203], off
.LBB0_1418:
	s_or_b64 exec, exec, s[2:3]
	v_add_u32_e32 v113, 0xa0, v121
	s_movk_i32 s0, 0x15f
	v_add_u32_e32 v62, s16, v113
	v_cmp_gt_i32_e64 s[4:5], s0, v121
	v_ashrrev_i32_e32 v63, 31, v62
	v_mov_b32_e32 v31, 0
	v_mov_b32_e32 v30, 0
	v_mov_b32_e32 v32, 0
	v_mov_b32_e32 v248, 0
	v_mov_b32_e32 v249, 0
	s_and_saveexec_b64 s[2:3], s[4:5]
	s_cbranch_execz .LBB0_1420
	v_lshlrev_b64 v[248:249], 9, v[62:63]
	v_lshl_add_u64 v[248:249], v[20:21], 0, v[248:249]
	global_load_dwordx2 v[248:249], v[248:249], off
.LBB0_1420:
	s_or_b64 exec, exec, s[2:3]
	v_add_u32_e32 v111, 0xc0, v121
	s_movk_i32 s0, 0x13f
	v_add_u32_e32 v64, s16, v111
	v_cmp_gt_i32_e64 s[2:3], s0, v121
	v_mov_b32_e32 v2, 0
	v_ashrrev_i32_e32 v65, 31, v64
	v_mov_b32_e32 v25, 0
	v_mov_b32_e32 v27, 0
	v_mov_b32_e32 v26, 0
	v_mov_b32_e32 v28, 0
	v_mov_b32_e32 v250, 0
	v_mov_b32_e32 v251, 0
	s_and_saveexec_b64 s[6:7], s[2:3]
	s_cbranch_execz .LBB0_1422
	v_lshlrev_b64 v[250:251], 9, v[64:65]
	v_lshl_add_u64 v[250:251], v[20:21], 0, v[250:251]
	global_load_dwordx2 v[250:251], v[250:251], off

.LBB0_1424:
	s_or_b64 exec, exec, s[6:7]
	s_waitcnt vmcnt(0)
	v_lshlrev_b32_e32 v33, 16, v202
	v_and_b32_e32 v35, 0xffff0000, v202
	v_lshlrev_b32_e32 v34, 16, v203
	v_and_b32_e32 v36, 0xffff0000, v203
	v_lshlrev_b32_e32 v29, 16, v248
	v_and_b32_e32 v31, 0xffff0000, v248
	v_lshlrev_b32_e32 v30, 16, v249
	v_and_b32_e32 v32, 0xffff0000, v249
	v_lshlrev_b32_e32 v25, 16, v250
	v_and_b32_e32 v27, 0xffff0000, v250
	v_lshlrev_b32_e32 v26, 16, v251
	v_and_b32_e32 v28, 0xffff0000, v251
	v_mul_f32_e32 v69, v17, v51
	v_mul_f32_e32 v70, v19, v68
	v_fmac_f32_e32 v69, v16, v49
	v_fmac_f32_e32 v70, v18, v50
	v_add_f32_e32 v69, v69, v70
	v_mul_f32_e32 v73, v9, v51
	v_mul_f32_e32 v70, v15, v68
	v_add_f32_dpp v69, v69, v69 quad_perm:[1,0,3,2] row_mask:0xf bank_mask:0xf bound_ctrl:1
	v_fmac_f32_e32 v73, v8, v49
	v_mul_f32_e32 v74, v11, v68
	v_add_f32_dpp v69, v69, v69 quad_perm:[2,3,0,1] row_mask:0xf bank_mask:0xf bound_ctrl:1
	v_fmac_f32_e32 v70, v14, v50
	v_fmac_f32_e32 v74, v10, v50
	v_add_f32_dpp v71, v69, v69 row_ror:4 row_mask:0xf bank_mask:0xf bound_ctrl:1
	v_mul_f32_e32 v69, v13, v51
	v_mul_f32_e32 v51, v5, v51
	v_fmac_f32_e32 v69, v12, v49
	v_fmac_f32_e32 v51, v4, v49
	v_mul_f32_e32 v49, v7, v68
	v_fmac_f32_e32 v49, v6, v50
	v_add_f32_e32 v69, v69, v70
	v_add_f32_e32 v73, v73, v74
	v_add_f32_e32 v49, v51, v49
	v_add_f32_dpp v69, v69, v69 quad_perm:[1,0,3,2] row_mask:0xf bank_mask:0xf bound_ctrl:1
	v_add_f32_dpp v73, v73, v73 quad_perm:[1,0,3,2] row_mask:0xf bank_mask:0xf bound_ctrl:1
	v_add_f32_dpp v49, v49, v49 quad_perm:[1,0,3,2] row_mask:0xf bank_mask:0xf bound_ctrl:1
	v_add_f32_dpp v69, v69, v69 quad_perm:[2,3,0,1] row_mask:0xf bank_mask:0xf bound_ctrl:1
	v_add_f32_dpp v73, v73, v73 quad_perm:[2,3,0,1] row_mask:0xf bank_mask:0xf bound_ctrl:1
	v_add_f32_dpp v49, v49, v49 quad_perm:[2,3,0,1] row_mask:0xf bank_mask:0xf bound_ctrl:1
	v_cmp_gt_u32_e64 s[40:41], 4, v147
	v_lshlrev_b32_e32 v225, 12, v147
	v_add_f32_dpp v69, v69, v69 row_ror:4 row_mask:0xf bank_mask:0xf bound_ctrl:1
	v_add_f32_dpp v73, v73, v73 row_ror:4 row_mask:0xf bank_mask:0xf bound_ctrl:1
	v_add_f32_dpp v50, v49, v49 row_ror:4 row_mask:0xf bank_mask:0xf bound_ctrl:1
	v_cmp_eq_u32_e64 s[38:39], 2, v147
	v_add_u32_e32 v155, 0, v225
	v_mov_b32_dpp v72, v71 row_ror:8 row_mask:0xf bank_mask:0xf bound_ctrl:1
	v_mov_b32_dpp v70, v69 row_ror:8 row_mask:0xf bank_mask:0xf bound_ctrl:1
	v_mov_b32_dpp v74, v73 row_ror:8 row_mask:0xf bank_mask:0xf bound_ctrl:1
	v_mov_b32_dpp v51, v50 row_ror:8 row_mask:0xf bank_mask:0xf bound_ctrl:1
	s_and_b64 s[0:1], s[56:57], s[40:41]
	s_and_saveexec_b64 s[20:21], s[0:1]
	s_cbranch_execz .LBB0_1432
	v_add_f32_e32 v49, v71, v72
	v_cmp_lt_i32_e64 s[6:7], 0, v147
	s_and_saveexec_b64 s[10:11], s[6:7]
	s_cbranch_execz .LBB0_1431
	v_cmp_ne_u32_e64 s[6:7], 1, v147
	s_and_saveexec_b64 s[0:1], s[6:7]
	s_xor_b64 s[0:1], exec, s[0:1]
	v_add_f32_e32 v49, v73, v74
	v_add_f32_e32 v50, v50, v51
	v_cndmask_b32_e64 v49, v50, v49, s[38:39]
	s_andn2_saveexec_b64 s[0:1], s[0:1]
	v_add_f32_e32 v49, v69, v70
	s_or_b64 exec, exec, s[0:1]

.LBB0_1488:
	s_or_b64 exec, exec, s[20:21]
	v_add_u32_e32 v143, 0x100, v121
	s_movk_i32 s0, 0xff
	v_add_u32_e32 v68, s16, v143
	v_cmp_gt_i32_e64 s[72:73], s0, v121
	v_mov_b32_e32 v45, 0
	v_ashrrev_i32_e32 v69, 31, v68
	v_mov_b32_e32 v49, 0
	v_mov_b32_e32 v51, 0
	v_mov_b32_e32 v50, 0
	v_mov_b32_e32 v84, 0
	v_mov_b32_e32 v202, 0
	v_mov_b32_e32 v203, 0
	s_and_saveexec_b64 s[6:7], s[72:73]
	s_cbranch_execz .LBB0_1490
	v_lshlrev_b64 v[202:203], 9, v[68:69]
	v_lshl_add_u64 v[202:203], v[20:21], 0, v[202:203]
	global_load_dwordx2 v[202:203], v[202:203], off
.LBB0_1490:
	s_or_b64 exec, exec, s[6:7]
	v_add_u32_e32 v141, 0x120, v121
	s_movk_i32 s0, 0xdf
	v_add_u32_e32 v70, s16, v141
	v_cmp_gt_i32_e64 s[70:71], s0, v121
	v_ashrrev_i32_e32 v71, 31, v70
	v_mov_b32_e32 v47, 0
	v_mov_b32_e32 v46, 0
	v_mov_b32_e32 v48, 0
	v_mov_b32_e32 v248, 0
	v_mov_b32_e32 v249, 0
	s_and_saveexec_b64 s[6:7], s[70:71]
	s_cbranch_execz .LBB0_1492
	v_lshlrev_b64 v[248:249], 9, v[70:71]
	v_lshl_add_u64 v[248:249], v[20:21], 0, v[248:249]
	global_load_dwordx2 v[248:249], v[248:249], off
.LBB0_1492:
	s_or_b64 exec, exec, s[6:7]
	v_add_u32_e32 v139, 0x140, v121
	s_movk_i32 s0, 0xbf
	v_add_u32_e32 v72, s16, v139
	v_cmp_gt_i32_e64 s[68:69], s0, v121
	v_mov_b32_e32 v37, 0
	v_ashrrev_i32_e32 v73, 31, v72
	v_mov_b32_e32 v41, 0
	v_mov_b32_e32 v43, 0
	v_mov_b32_e32 v42, 0
	v_mov_b32_e32 v44, 0
	v_mov_b32_e32 v250, 0
	v_mov_b32_e32 v251, 0
	s_and_saveexec_b64 s[6:7], s[68:69]
	s_cbranch_execz .LBB0_1494
	v_lshlrev_b64 v[250:251], 9, v[72:73]
	v_lshl_add_u64 v[250:251], v[20:21], 0, v[250:251]
	global_load_dwordx2 v[250:251], v[250:251], off

.LBB0_1496:
	s_or_b64 exec, exec, s[6:7]
	s_waitcnt vmcnt(0)
	v_lshlrev_b32_e32 v49, 16, v202
	v_and_b32_e32 v51, 0xffff0000, v202
	v_lshlrev_b32_e32 v50, 16, v203
	v_and_b32_e32 v84, 0xffff0000, v203
	v_lshlrev_b32_e32 v45, 16, v248
	v_and_b32_e32 v47, 0xffff0000, v248
	v_lshlrev_b32_e32 v46, 16, v249
	v_and_b32_e32 v48, 0xffff0000, v249
	v_lshlrev_b32_e32 v41, 16, v250
	v_and_b32_e32 v43, 0xffff0000, v250
	v_lshlrev_b32_e32 v42, 16, v251
	v_and_b32_e32 v44, 0xffff0000, v251
	v_add_u32_e32 v135, 0x180, v121
	s_movk_i32 s0, 0x7f
	v_add_u32_e32 v76, s16, v135
	v_cmp_gt_i32_e64 s[64:65], s0, v121
	v_mov_b32_e32 v29, 0
	v_ashrrev_i32_e32 v77, 31, v76
	v_mov_b32_e32 v33, 0
	v_mov_b32_e32 v35, 0
	v_mov_b32_e32 v34, 0
	v_mov_b32_e32 v36, 0
	v_mov_b32_e32 v202, 0
	v_mov_b32_e32 v203, 0
	s_and_saveexec_b64 s[6:7], s[64:65]
	s_cbranch_execz .LBB0_1498
	v_lshlrev_b64 v[202:203], 9, v[76:77]
	v_lshl_add_u64 v[202:203], v[20:21], 0, v[202:203]
	global_load_dwordx2 v[202:203], v[202:203], off
.LBB0_1498:
	s_or_b64 exec, exec, s[6:7]
	v_add_u32_e32 v133, 0x1a0, v121
	s_movk_i32 s0, 0x5f
	v_add_u32_e32 v78, s16, v133
	v_cmp_gt_i32_e64 s[62:63], s0, v121
	v_ashrrev_i32_e32 v79, 31, v78
	v_mov_b32_e32 v31, 0
	v_mov_b32_e32 v30, 0
	v_mov_b32_e32 v32, 0
	v_mov_b32_e32 v248, 0
	v_mov_b32_e32 v249, 0
	s_and_saveexec_b64 s[6:7], s[62:63]
	s_cbranch_execz .LBB0_1500
	v_lshlrev_b64 v[248:249], 9, v[78:79]
	v_lshl_add_u64 v[248:249], v[20:21], 0, v[248:249]
	global_load_dwordx2 v[248:249], v[248:249], off
.LBB0_1500:
	s_or_b64 exec, exec, s[6:7]
	v_add_u32_e32 v131, 0x1c0, v121
	v_add_u32_e32 v80, s16, v131
	v_cmp_gt_i32_e64 s[60:61], 63, v121
	v_mov_b32_e32 v2, 0
	v_ashrrev_i32_e32 v81, 31, v80
	v_mov_b32_e32 v25, 0
	v_mov_b32_e32 v27, 0
	v_mov_b32_e32 v26, 0
	v_mov_b32_e32 v28, 0
	v_mov_b32_e32 v250, 0
	v_mov_b32_e32 v251, 0
	s_and_saveexec_b64 s[6:7], s[60:61]
	s_cbranch_execz .LBB0_1502
	v_lshlrev_b64 v[250:251], 9, v[80:81]
	v_lshl_add_u64 v[250:251], v[20:21], 0, v[250:251]
	global_load_dwordx2 v[250:251], v[250:251], off

.LBB0_1504:
	s_or_b64 exec, exec, s[6:7]
	s_waitcnt vmcnt(0)
	v_lshlrev_b32_e32 v33, 16, v202
	v_and_b32_e32 v35, 0xffff0000, v202
	v_lshlrev_b32_e32 v34, 16, v203
	v_and_b32_e32 v36, 0xffff0000, v203
	v_lshlrev_b32_e32 v29, 16, v248
	v_and_b32_e32 v31, 0xffff0000, v248
	v_lshlrev_b32_e32 v30, 16, v249
	v_and_b32_e32 v32, 0xffff0000, v249
	v_lshlrev_b32_e32 v25, 16, v250
	v_and_b32_e32 v27, 0xffff0000, v250
	v_lshlrev_b32_e32 v26, 16, v251
	v_and_b32_e32 v28, 0xffff0000, v251
	v_mul_f32_e32 v20, v17, v51
	v_mul_f32_e32 v85, v13, v51
	v_mul_f32_e32 v87, v9, v51
	v_mul_f32_e32 v51, v5, v51
	v_fmac_f32_e32 v20, v16, v49
	v_mul_f32_e32 v21, v19, v84
	v_fmac_f32_e32 v85, v12, v49
	v_mul_f32_e32 v86, v15, v84
	v_fmac_f32_e32 v87, v8, v49
	v_mul_f32_e32 v88, v11, v84
	v_fmac_f32_e32 v51, v4, v49
	v_mul_f32_e32 v49, v7, v84
	v_fmac_f32_e32 v21, v18, v50
	v_fmac_f32_e32 v86, v14, v50
	v_fmac_f32_e32 v88, v10, v50
	v_fmac_f32_e32 v49, v6, v50
	v_add_f32_e32 v20, v20, v21
	v_add_f32_e32 v85, v85, v86
	v_add_f32_e32 v87, v87, v88
	v_add_f32_e32 v49, v51, v49
	v_add_f32_dpp v20, v20, v20 quad_perm:[1,0,3,2] row_mask:0xf bank_mask:0xf bound_ctrl:1
	v_add_f32_dpp v85, v85, v85 quad_perm:[1,0,3,2] row_mask:0xf bank_mask:0xf bound_ctrl:1
	v_add_f32_dpp v87, v87, v87 quad_perm:[1,0,3,2] row_mask:0xf bank_mask:0xf bound_ctrl:1
	v_add_f32_dpp v49, v49, v49 quad_perm:[1,0,3,2] row_mask:0xf bank_mask:0xf bound_ctrl:1
	v_add_f32_dpp v20, v20, v20 quad_perm:[2,3,0,1] row_mask:0xf bank_mask:0xf bound_ctrl:1
	v_add_f32_dpp v85, v85, v85 quad_perm:[2,3,0,1] row_mask:0xf bank_mask:0xf bound_ctrl:1
	v_add_f32_dpp v87, v87, v87 quad_perm:[2,3,0,1] row_mask:0xf bank_mask:0xf bound_ctrl:1
	v_add_f32_dpp v49, v49, v49 quad_perm:[2,3,0,1] row_mask:0xf bank_mask:0xf bound_ctrl:1
	v_add_f32_dpp v20, v20, v20 row_ror:4 row_mask:0xf bank_mask:0xf bound_ctrl:1
	v_add_f32_dpp v85, v85, v85 row_ror:4 row_mask:0xf bank_mask:0xf bound_ctrl:1
	v_add_f32_dpp v87, v87, v87 row_ror:4 row_mask:0xf bank_mask:0xf bound_ctrl:1
	v_add_f32_dpp v50, v49, v49 row_ror:4 row_mask:0xf bank_mask:0xf bound_ctrl:1
	v_mov_b32_dpp v21, v20 row_ror:8 row_mask:0xf bank_mask:0xf bound_ctrl:1
	v_mov_b32_dpp v86, v85 row_ror:8 row_mask:0xf bank_mask:0xf bound_ctrl:1
	v_mov_b32_dpp v88, v87 row_ror:8 row_mask:0xf bank_mask:0xf bound_ctrl:1
	v_mov_b32_dpp v51, v50 row_ror:8 row_mask:0xf bank_mask:0xf bound_ctrl:1
	s_and_b64 s[0:1], s[72:73], s[40:41]
	s_and_saveexec_b64 s[20:21], s[0:1]
	s_cbranch_execz .LBB0_1512
	v_cmp_lt_i32_e64 s[6:7], 0, v147
	s_and_saveexec_b64 s[0:1], s[6:7]
	s_xor_b64 s[10:11], exec, s[0:1]
	s_cbranch_execz .LBB0_1509
	v_add_f32_e32 v49, v85, v86
	v_cmp_ne_u32_e64 s[6:7], 1, v147
	s_and_saveexec_b64 s[0:1], s[6:7]
	v_add_f32_e32 v20, v87, v88
	v_add_f32_e32 v21, v50, v51
	v_cndmask_b32_e64 v49, v21, v20, s[38:39]
	s_or_b64 exec, exec, s[0:1]

.LBB0_1580:
	s_or_b64 exec, exec, s[0:1]
	s_waitcnt lgkmcnt(0)
	s_barrier
	ds_read_b128 v[44:47], v3 offset:19456
	ds_read_b128 v[48:51], v3 offset:19472
	ds_read_b128 v[40:43], v3 offset:19488
	ds_read_b128 v[36:39], v3 offset:19504
	ds_read_b128 v[32:35], v3 offset:19520
	ds_read_b128 v[28:31], v3 offset:19536
	ds_read_b128 v[24:27], v3 offset:19552
	ds_read_b128 v[20:23], v3 offset:19568
	s_add_u32 s0, s88, s8
	s_addc_u32 s1, s89, 0
	v_lshlrev_b32_e32 v2, 1, v103
	v_lshl_add_u64 v[160:161], s[0:1], 0, v[2:3]
	v_mov_b32_e32 v84, 0
	v_mov_b32_e32 v86, 0
	v_mov_b32_e32 v87, 0
	v_mov_b32_e32 v88, 0
	v_mov_b32_e32 v89, 0
	s_waitcnt lgkmcnt(0)
	s_barrier
	v_mov_b32_e32 v202, 0
	v_mov_b32_e32 v203, 0
	s_and_saveexec_b64 s[6:7], s[56:57]
	s_cbranch_execz .LBB0_1582
	v_lshlrev_b64 v[202:203], 9, v[52:53]
	v_lshl_add_u64 v[202:203], v[160:161], 0, v[202:203]
	global_load_dwordx2 v[202:203], v[202:203], off
.LBB0_1582:
	s_or_b64 exec, exec, s[6:7]
	v_mov_b32_e32 v85, 0
	v_mov_b32_e32 v52, 0
	v_mov_b32_e32 v53, 0
	v_mov_b32_e32 v248, 0
	v_mov_b32_e32 v249, 0
	s_and_saveexec_b64 s[6:7], s[54:55]
	s_cbranch_execz .LBB0_1584
	v_lshlrev_b64 v[248:249], 9, v[54:55]
	v_lshl_add_u64 v[248:249], v[160:161], 0, v[248:249]
	global_load_dwordx2 v[248:249], v[248:249], off
.LBB0_1584:
	s_or_b64 exec, exec, s[6:7]
	v_mov_b32_e32 v54, 0
	v_mov_b32_e32 v90, 0
	v_mov_b32_e32 v91, 0
	v_mov_b32_e32 v92, 0
	v_mov_b32_e32 v93, 0
	v_mov_b32_e32 v250, 0
	v_mov_b32_e32 v251, 0
	s_and_saveexec_b64 s[6:7], s[52:53]
	s_cbranch_execz .LBB0_1586
	v_lshlrev_b64 v[250:251], 9, v[56:57]
	v_lshl_add_u64 v[250:251], v[160:161], 0, v[250:251]
	global_load_dwordx2 v[250:251], v[250:251], off

.LBB0_1588:
	s_or_b64 exec, exec, s[6:7]
	s_waitcnt vmcnt(0)
	v_lshlrev_b32_e32 v86, 16, v202
	v_and_b32_e32 v87, 0xffff0000, v202
	v_lshlrev_b32_e32 v88, 16, v203
	v_and_b32_e32 v89, 0xffff0000, v203
	v_lshlrev_b32_e32 v84, 16, v248
	v_and_b32_e32 v85, 0xffff0000, v248
	v_lshlrev_b32_e32 v52, 16, v249
	v_and_b32_e32 v53, 0xffff0000, v249
	v_lshlrev_b32_e32 v90, 16, v250
	v_and_b32_e32 v91, 0xffff0000, v250
	v_lshlrev_b32_e32 v92, 16, v251
	v_and_b32_e32 v93, 0xffff0000, v251
	v_mov_b32_e32 v58, 0
	v_mov_b32_e32 v94, 0
	v_mov_b32_e32 v95, 0
	v_mov_b32_e32 v96, 0
	v_mov_b32_e32 v97, 0
	v_mov_b32_e32 v202, 0
	v_mov_b32_e32 v203, 0
	s_and_saveexec_b64 s[6:7], s[46:47]
	s_cbranch_execz .LBB0_1590
	v_lshlrev_b64 v[202:203], 9, v[60:61]
	v_lshl_add_u64 v[202:203], v[160:161], 0, v[202:203]
	global_load_dwordx2 v[202:203], v[202:203], off
.LBB0_1590:
	s_or_b64 exec, exec, s[6:7]
	v_mov_b32_e32 v59, 0
	v_mov_b32_e32 v60, 0
	v_mov_b32_e32 v61, 0
	v_mov_b32_e32 v248, 0
	v_mov_b32_e32 v249, 0
	s_and_saveexec_b64 s[6:7], s[4:5]
	s_cbranch_execz .LBB0_1592
	v_lshlrev_b64 v[58:59], 9, v[62:63]
	v_lshl_add_u64 v[58:59], v[160:161], 0, v[58:59]
	global_load_dwordx2 v[248:249], v[58:59], off
.LBB0_1592:
	s_or_b64 exec, exec, s[6:7]
	v_mov_b32_e32 v62, 0
	v_mov_b32_e32 v98, 0
	v_mov_b32_e32 v99, 0
	v_mov_b32_e32 v100, 0
	v_mov_b32_e32 v101, 0
	v_mov_b32_e32 v250, 0
	v_mov_b32_e32 v251, 0
	s_and_saveexec_b64 s[6:7], s[2:3]
	s_cbranch_execz .LBB0_1594
	v_lshlrev_b64 v[250:251], 9, v[64:65]
	v_lshl_add_u64 v[250:251], v[160:161], 0, v[250:251]
	global_load_dwordx2 v[250:251], v[250:251], off

.LBB0_1596:
	s_or_b64 exec, exec, s[6:7]
	s_waitcnt vmcnt(0)
	v_lshlrev_b32_e32 v94, 16, v202
	v_and_b32_e32 v95, 0xffff0000, v202
	v_lshlrev_b32_e32 v96, 16, v203
	v_and_b32_e32 v97, 0xffff0000, v203
	v_lshlrev_b32_e32 v58, 16, v248
	v_and_b32_e32 v59, 0xffff0000, v248
	v_lshlrev_b32_e32 v60, 16, v249
	v_and_b32_e32 v61, 0xffff0000, v249
	v_lshlrev_b32_e32 v98, 16, v250
	v_and_b32_e32 v99, 0xffff0000, v250
	v_lshlrev_b32_e32 v100, 16, v251
	v_and_b32_e32 v101, 0xffff0000, v251
	v_min_i32_e32 v2, 0x3ff, v121
	v_lshl_add_u32 v205, v2, 2, 0
	v_mov_b32_e32 v104, 0
	v_mov_b32_e32 v66, 0
	s_and_saveexec_b64 s[0:1], s[56:57]
	ds_read_b32 v66, v205 offset:1024
	s_or_b64 exec, exec, s[0:1]
	s_and_saveexec_b64 s[0:1], s[56:57]
	ds_read_b32 v104, v205 offset:5120
	s_or_b64 exec, exec, s[0:1]
	v_mov_b32_e32 v2, 0
	v_mov_b32_e32 v120, 0
	s_and_saveexec_b64 s[0:1], s[56:57]
	ds_read_b32 v120, v205 offset:9216
	s_or_b64 exec, exec, s[0:1]
	s_and_saveexec_b64 s[0:1], s[56:57]
	ds_read_b32 v2, v205 offset:13312
	s_or_b64 exec, exec, s[0:1]
	v_min_i32_e32 v67, 0x3ff, v123
	v_lshl_add_u32 v209, v67, 2, 0
	v_mov_b32_e32 v110, 0
	v_mov_b32_e32 v106, 0
	s_and_saveexec_b64 s[0:1], s[54:55]
	ds_read_b32 v106, v209 offset:1024
	s_or_b64 exec, exec, s[0:1]
	s_and_saveexec_b64 s[0:1], s[54:55]
	ds_read_b32 v110, v209 offset:5120
	s_or_b64 exec, exec, s[0:1]
	v_mov_b32_e32 v102, 0
	v_mov_b32_e32 v128, 0
	s_and_saveexec_b64 s[0:1], s[54:55]
	ds_read_b32 v128, v209 offset:9216
	s_or_b64 exec, exec, s[0:1]
	s_and_saveexec_b64 s[0:1], s[54:55]
	ds_read_b32 v102, v209 offset:13312
	s_or_b64 exec, exec, s[0:1]
	v_min_i32_e32 v67, 0x3ff, v119
	v_lshl_add_u32 v211, v67, 2, 0
	v_mov_b32_e32 v116, 0
	v_mov_b32_e32 v112, 0
	s_and_saveexec_b64 s[0:1], s[52:53]
	ds_read_b32 v112, v211 offset:1024
	s_or_b64 exec, exec, s[0:1]
	s_and_saveexec_b64 s[0:1], s[52:53]
	ds_read_b32 v116, v211 offset:5120
	s_or_b64 exec, exec, s[0:1]
	v_mov_b32_e32 v108, 0
	v_mov_b32_e32 v136, 0
	s_and_saveexec_b64 s[0:1], s[52:53]
	ds_read_b32 v136, v211 offset:9216
	s_or_b64 exec, exec, s[0:1]
	s_and_saveexec_b64 s[0:1], s[52:53]
	ds_read_b32 v108, v211 offset:13312
	s_or_b64 exec, exec, s[0:1]
	v_min_i32_e32 v67, 0x3ff, v117
	v_lshl_add_u32 v213, v67, 2, 0
	v_mov_b32_e32 v124, 0
	v_mov_b32_e32 v118, 0
	s_and_saveexec_b64 s[0:1], s[48:49]
	ds_read_b32 v118, v213 offset:1024
	s_or_b64 exec, exec, s[0:1]
	s_and_saveexec_b64 s[0:1], s[48:49]
	ds_read_b32 v124, v213 offset:5120
	s_or_b64 exec, exec, s[0:1]
	v_mov_b32_e32 v114, 0
	v_mov_b32_e32 v144, 0
	s_and_saveexec_b64 s[0:1], s[48:49]
	ds_read_b32 v144, v213 offset:9216
	s_or_b64 exec, exec, s[0:1]
	s_and_saveexec_b64 s[0:1], s[48:49]
	ds_read_b32 v114, v213 offset:13312
	s_or_b64 exec, exec, s[0:1]
	v_min_i32_e32 v67, 0x3ff, v115
	v_lshl_add_u32 v215, v67, 2, 0
	v_mov_b32_e32 v132, 0
	v_mov_b32_e32 v126, 0
	s_and_saveexec_b64 s[0:1], s[46:47]
	ds_read_b32 v126, v215 offset:1024
	s_or_b64 exec, exec, s[0:1]
	s_and_saveexec_b64 s[0:1], s[46:47]
	ds_read_b32 v132, v215 offset:5120
	s_or_b64 exec, exec, s[0:1]
	v_mov_b32_e32 v122, 0
	v_mov_b32_e32 v154, 0
	s_and_saveexec_b64 s[0:1], s[46:47]
	ds_read_b32 v154, v215 offset:9216
	s_or_b64 exec, exec, s[0:1]
	s_and_saveexec_b64 s[0:1], s[46:47]
	ds_read_b32 v122, v215 offset:13312
	s_or_b64 exec, exec, s[0:1]
	v_min_i32_e32 v67, 0x3ff, v113
	v_lshl_add_u32 v217, v67, 2, 0
	v_mov_b32_e32 v140, 0
	v_mov_b32_e32 v134, 0
	s_and_saveexec_b64 s[0:1], s[4:5]
	ds_read_b32 v134, v217 offset:1024
	s_or_b64 exec, exec, s[0:1]
	s_and_saveexec_b64 s[0:1], s[4:5]
	ds_read_b32 v140, v217 offset:5120
	s_or_b64 exec, exec, s[0:1]
	v_mov_b32_e32 v130, 0
	v_mov_b32_e32 v164, 0
	s_and_saveexec_b64 s[0:1], s[4:5]
	ds_read_b32 v164, v217 offset:9216
	s_or_b64 exec, exec, s[0:1]
	s_and_saveexec_b64 s[0:1], s[4:5]
	ds_read_b32 v130, v217 offset:13312
	s_or_b64 exec, exec, s[0:1]
	v_min_i32_e32 v67, 0x3ff, v111
	v_lshl_add_u32 v219, v67, 2, 0
	v_mov_b32_e32 v148, 0
	v_mov_b32_e32 v142, 0
	s_and_saveexec_b64 s[0:1], s[2:3]
	ds_read_b32 v142, v219 offset:1024
	s_or_b64 exec, exec, s[0:1]
	s_and_saveexec_b64 s[0:1], s[2:3]
	ds_read_b32 v148, v219 offset:5120
	s_or_b64 exec, exec, s[0:1]
	v_mov_b32_e32 v138, 0
	v_mov_b32_e32 v170, 0
	s_and_saveexec_b64 s[0:1], s[2:3]
	ds_read_b32 v170, v219 offset:9216
	s_or_b64 exec, exec, s[0:1]
	s_and_saveexec_b64 s[0:1], s[2:3]
	ds_read_b32 v138, v219 offset:13312
	s_or_b64 exec, exec, s[0:1]
	v_min_i32_e32 v67, 0x3ff, v109
	v_lshl_add_u32 v221, v67, 2, 0
	v_mov_b32_e32 v162, 0
	v_mov_b32_e32 v150, 0
	s_and_saveexec_b64 s[0:1], vcc
	ds_read_b32 v150, v221 offset:1024
	s_or_b64 exec, exec, s[0:1]
	s_and_saveexec_b64 s[0:1], vcc
	ds_read_b32 v162, v221 offset:5120
	s_or_b64 exec, exec, s[0:1]
	v_mov_b32_e32 v146, 0
	v_mov_b32_e32 v176, 0
	s_and_saveexec_b64 s[0:1], vcc
	ds_read_b32 v176, v221 offset:9216
	s_or_b64 exec, exec, s[0:1]
	s_and_saveexec_b64 s[0:1], vcc
	ds_read_b32 v146, v221 offset:13312
	s_or_b64 exec, exec, s[0:1]
	v_mov_b32_e32 v152, 0
	v_mov_b32_e32 v156, 0
	v_mov_b32_e32 v157, 0
	v_mov_b32_e32 v158, 0
	v_mov_b32_e32 v159, 0
	v_mov_b32_e32 v202, 0
	v_mov_b32_e32 v203, 0
	s_and_saveexec_b64 s[2:3], s[72:73]
	s_cbranch_execz .LBB0_1662
	v_lshlrev_b64 v[202:203], 9, v[68:69]
	v_lshl_add_u64 v[202:203], v[160:161], 0, v[202:203]
	global_load_dwordx2 v[202:203], v[202:203], off
.LBB0_1662:
	s_or_b64 exec, exec, s[2:3]
	v_mov_b32_e32 v153, 0
	v_mov_b32_e32 v68, 0
	v_mov_b32_e32 v69, 0
	v_mov_b32_e32 v248, 0
	v_mov_b32_e32 v249, 0
	s_and_saveexec_b64 s[2:3], s[70:71]
	s_cbranch_execz .LBB0_1664
	v_lshlrev_b64 v[248:249], 9, v[70:71]
	v_lshl_add_u64 v[248:249], v[160:161], 0, v[248:249]
	global_load_dwordx2 v[248:249], v[248:249], off
.LBB0_1664:
	s_or_b64 exec, exec, s[2:3]
	v_mov_b32_e32 v70, 0
	v_mov_b32_e32 v166, 0
	v_mov_b32_e32 v167, 0
	v_mov_b32_e32 v168, 0
	v_mov_b32_e32 v169, 0
	v_mov_b32_e32 v250, 0
	v_mov_b32_e32 v251, 0
	s_and_saveexec_b64 s[2:3], s[68:69]
	s_cbranch_execz .LBB0_1666
	v_lshlrev_b64 v[250:251], 9, v[72:73]
	v_lshl_add_u64 v[250:251], v[160:161], 0, v[250:251]
	global_load_dwordx2 v[250:251], v[250:251], off

.LBB0_1668:
	s_or_b64 exec, exec, s[2:3]
	s_waitcnt vmcnt(0)
	v_lshlrev_b32_e32 v156, 16, v202
	v_and_b32_e32 v157, 0xffff0000, v202
	v_lshlrev_b32_e32 v158, 16, v203
	v_and_b32_e32 v159, 0xffff0000, v203
	v_lshlrev_b32_e32 v152, 16, v248
	v_and_b32_e32 v153, 0xffff0000, v248
	v_lshlrev_b32_e32 v68, 16, v249
	v_and_b32_e32 v69, 0xffff0000, v249
	v_lshlrev_b32_e32 v166, 16, v250
	v_and_b32_e32 v167, 0xffff0000, v250
	v_lshlrev_b32_e32 v168, 16, v251
	v_and_b32_e32 v169, 0xffff0000, v251
	v_mov_b32_e32 v74, 0
	v_mov_b32_e32 v172, 0
	v_mov_b32_e32 v173, 0
	v_mov_b32_e32 v174, 0
	v_mov_b32_e32 v175, 0
	v_mov_b32_e32 v202, 0
	v_mov_b32_e32 v203, 0
	s_and_saveexec_b64 s[2:3], s[64:65]
	s_cbranch_execz .LBB0_1670
	v_lshlrev_b64 v[202:203], 9, v[76:77]
	v_lshl_add_u64 v[202:203], v[160:161], 0, v[202:203]
	global_load_dwordx2 v[202:203], v[202:203], off
.LBB0_1670:
	s_or_b64 exec, exec, s[2:3]
	v_mov_b32_e32 v75, 0
	v_mov_b32_e32 v76, 0
	v_mov_b32_e32 v77, 0
	v_mov_b32_e32 v248, 0
	v_mov_b32_e32 v249, 0
	s_and_saveexec_b64 s[2:3], s[62:63]
	s_cbranch_execz .LBB0_1672
	v_lshlrev_b64 v[74:75], 9, v[78:79]
	v_lshl_add_u64 v[74:75], v[160:161], 0, v[74:75]
	global_load_dwordx2 v[248:249], v[74:75], off
.LBB0_1672:
	s_or_b64 exec, exec, s[2:3]
	v_mov_b32_e32 v78, 0
	v_mov_b32_e32 v178, 0
	v_mov_b32_e32 v179, 0
	v_mov_b32_e32 v180, 0
	v_mov_b32_e32 v181, 0
	v_mov_b32_e32 v250, 0
	v_mov_b32_e32 v251, 0
	s_and_saveexec_b64 s[2:3], s[60:61]
	s_cbranch_execz .LBB0_1674
	v_lshlrev_b64 v[250:251], 9, v[80:81]
	v_lshl_add_u64 v[250:251], v[160:161], 0, v[250:251]
	global_load_dwordx2 v[250:251], v[250:251], off

.LBB0_1676:
	s_or_b64 exec, exec, s[2:3]
	s_waitcnt vmcnt(0)
	v_lshlrev_b32_e32 v172, 16, v202
	v_and_b32_e32 v173, 0xffff0000, v202
	v_lshlrev_b32_e32 v174, 16, v203
	v_and_b32_e32 v175, 0xffff0000, v203
	v_lshlrev_b32_e32 v74, 16, v248
	v_and_b32_e32 v75, 0xffff0000, v248
	v_lshlrev_b32_e32 v76, 16, v249
	v_and_b32_e32 v77, 0xffff0000, v249
	v_lshlrev_b32_e32 v178, 16, v250
	v_and_b32_e32 v179, 0xffff0000, v250
	v_lshlrev_b32_e32 v180, 16, v251
	v_and_b32_e32 v181, 0xffff0000, v251
	v_min_i32_e32 v67, 0x3ff, v143
	v_lshl_add_u32 v161, v67, 2, 0
	v_mov_b32_e32 v184, 0
	v_mov_b32_e32 v160, 0
	s_and_saveexec_b64 s[0:1], s[72:73]
	ds_read_b32 v160, v161 offset:1024
	s_or_b64 exec, exec, s[0:1]
	s_and_saveexec_b64 s[0:1], s[72:73]
	ds_read_b32 v184, v161 offset:5120
	s_or_b64 exec, exec, s[0:1]
	v_mov_b32_e32 v82, 0
	v_mov_b32_e32 v196, 0
	s_and_saveexec_b64 s[0:1], s[72:73]
	ds_read_b32 v196, v161 offset:9216
	s_or_b64 exec, exec, s[0:1]
	s_and_saveexec_b64 s[0:1], s[72:73]
	ds_read_b32 v82, v161 offset:13312
	s_or_b64 exec, exec, s[0:1]
	v_min_i32_e32 v67, 0x3ff, v141
	v_lshl_add_u32 v185, v67, 2, 0
	v_mov_b32_e32 v190, 0
	v_mov_b32_e32 v186, 0
	s_and_saveexec_b64 s[0:1], s[70:71]
	ds_read_b32 v186, v185 offset:1024
	s_or_b64 exec, exec, s[0:1]
	s_and_saveexec_b64 s[0:1], s[70:71]
	ds_read_b32 v190, v185 offset:5120
	s_or_b64 exec, exec, s[0:1]
	v_mov_b32_e32 v182, 0
	v_mov_b32_e32 v210, 0
	s_and_saveexec_b64 s[0:1], s[70:71]
	ds_read_b32 v210, v185 offset:9216
	s_or_b64 exec, exec, s[0:1]
	s_and_saveexec_b64 s[0:1], s[70:71]
	ds_read_b32 v182, v185 offset:13312
	s_or_b64 exec, exec, s[0:1]
	v_min_i32_e32 v67, 0x3ff, v139
	v_lshl_add_u32 v187, v67, 2, 0
	v_mov_b32_e32 v204, 0
	v_mov_b32_e32 v192, 0
	s_and_saveexec_b64 s[0:1], s[68:69]
	ds_read_b32 v192, v187 offset:1024
	s_or_b64 exec, exec, s[0:1]
	s_and_saveexec_b64 s[0:1], s[68:69]
	ds_read_b32 v204, v187 offset:5120
	s_or_b64 exec, exec, s[0:1]
	v_mov_b32_e32 v188, 0
	v_mov_b32_e32 v218, 0
	s_and_saveexec_b64 s[0:1], s[68:69]
	ds_read_b32 v218, v187 offset:9216
	s_or_b64 exec, exec, s[0:1]
	s_and_saveexec_b64 s[0:1], s[68:69]
	ds_read_b32 v188, v187 offset:13312
	s_or_b64 exec, exec, s[0:1]
	v_min_i32_e32 v67, 0x3ff, v137
	v_lshl_add_u32 v189, v67, 2, 0
	v_mov_b32_e32 v212, 0
	v_mov_b32_e32 v206, 0
	s_and_saveexec_b64 s[0:1], s[66:67]
	ds_read_b32 v206, v189 offset:1024
	s_or_b64 exec, exec, s[0:1]
	s_and_saveexec_b64 s[0:1], s[66:67]
	ds_read_b32 v212, v189 offset:5120
	s_or_b64 exec, exec, s[0:1]
	v_mov_b32_e32 v194, 0
	v_mov_b32_e32 v226, 0
	s_and_saveexec_b64 s[0:1], s[66:67]
	ds_read_b32 v226, v189 offset:9216
	s_or_b64 exec, exec, s[0:1]
	s_and_saveexec_b64 s[0:1], s[66:67]
	ds_read_b32 v194, v189 offset:13312
	s_or_b64 exec, exec, s[0:1]
	v_min_i32_e32 v67, 0x3ff, v135
	v_lshl_add_u32 v191, v67, 2, 0
	v_mov_b32_e32 v220, 0
	v_mov_b32_e32 v214, 0
	s_and_saveexec_b64 s[0:1], s[64:65]
	ds_read_b32 v214, v191 offset:1024
	s_or_b64 exec, exec, s[0:1]
	s_and_saveexec_b64 s[0:1], s[64:65]
	ds_read_b32 v220, v191 offset:5120
	s_or_b64 exec, exec, s[0:1]
	v_mov_b32_e32 v208, 0
	v_mov_b32_e32 v234, 0
	s_and_saveexec_b64 s[0:1], s[64:65]
	ds_read_b32 v234, v191 offset:9216
	s_or_b64 exec, exec, s[0:1]
	s_and_saveexec_b64 s[0:1], s[64:65]
	ds_read_b32 v208, v191 offset:13312
	s_or_b64 exec, exec, s[0:1]
	v_min_i32_e32 v67, 0x3ff, v133
	v_lshl_add_u32 v193, v67, 2, 0
	v_mov_b32_e32 v228, 0
	v_mov_b32_e32 v222, 0
	s_and_saveexec_b64 s[0:1], s[62:63]
	ds_read_b32 v222, v193 offset:1024
	s_or_b64 exec, exec, s[0:1]
	s_and_saveexec_b64 s[0:1], s[62:63]
	ds_read_b32 v228, v193 offset:5120
	s_or_b64 exec, exec, s[0:1]
	v_mov_b32_e32 v216, 0
	v_mov_b32_e32 v240, 0
	s_and_saveexec_b64 s[0:1], s[62:63]
	ds_read_b32 v240, v193 offset:9216
	s_or_b64 exec, exec, s[0:1]
	s_and_saveexec_b64 s[0:1], s[62:63]
	ds_read_b32 v216, v193 offset:13312
	s_or_b64 exec, exec, s[0:1]
	v_min_i32_e32 v67, 0x3ff, v131
	v_lshl_add_u32 v195, v67, 2, 0
	v_mov_b32_e32 v236, 0
	v_mov_b32_e32 v230, 0
	s_and_saveexec_b64 s[0:1], s[60:61]
	ds_read_b32 v230, v195 offset:1024
	s_or_b64 exec, exec, s[0:1]
	s_and_saveexec_b64 s[0:1], s[60:61]
	ds_read_b32 v236, v195 offset:5120
	s_or_b64 exec, exec, s[0:1]
	v_mov_b32_e32 v224, 0
	v_mov_b32_e32 v244, 0
	s_and_saveexec_b64 s[0:1], s[60:61]
	ds_read_b32 v244, v195 offset:9216
	s_or_b64 exec, exec, s[0:1]
	s_and_saveexec_b64 s[0:1], s[60:61]
	ds_read_b32 v224, v195 offset:13312
	s_or_b64 exec, exec, s[0:1]
	v_min_i32_e32 v67, 0x3ff, v129
	v_lshl_add_u32 v197, v67, 2, 0
	v_mov_b32_e32 v242, 0
	v_mov_b32_e32 v238, 0
	s_and_saveexec_b64 s[0:1], s[58:59]
	ds_read_b32 v238, v197 offset:1024
	s_or_b64 exec, exec, s[0:1]
	s_and_saveexec_b64 s[0:1], s[58:59]
	ds_read_b32 v242, v197 offset:5120
	s_or_b64 exec, exec, s[0:1]
	v_mov_b32_e32 v232, 0
	v_mov_b32_e32 v246, 0
	s_and_saveexec_b64 s[0:1], s[58:59]
	ds_read_b32 v246, v197 offset:9216
	s_or_b64 exec, exec, s[0:1]
	s_and_saveexec_b64 s[0:1], s[58:59]
	ds_read_b32 v232, v197 offset:13312
	s_or_b64 exec, exec, s[0:1]
	s_waitcnt lgkmcnt(0)
	v_pk_fma_f32 v[198:199], v[86:87], v[120:121], 0 op_sel_hi:[1,0,0]
	v_pk_fma_f32 v[200:201], v[88:89], v[120:121], 0 op_sel_hi:[1,0,0]
	v_pk_fma_f32 v[198:199], v[84:85], v[128:129], v[198:199] op_sel_hi:[1,0,1]
	v_pk_fma_f32 v[200:201], v[52:53], v[128:129], v[200:201] op_sel_hi:[1,0,1]
	v_pk_fma_f32 v[198:199], v[90:91], v[136:137], v[198:199] op_sel_hi:[1,0,1]
	v_pk_fma_f32 v[200:201], v[92:93], v[136:137], v[200:201] op_sel_hi:[1,0,1]
	v_pk_fma_f32 v[198:199], v[54:55], v[144:145], v[198:199] op_sel_hi:[1,0,1]
	v_pk_fma_f32 v[200:201], v[56:57], v[144:145], v[200:201] op_sel_hi:[1,0,1]
	v_pk_fma_f32 v[198:199], v[94:95], v[154:155], v[198:199] op_sel_hi:[1,0,1]
	v_pk_fma_f32 v[200:201], v[96:97], v[154:155], v[200:201] op_sel_hi:[1,0,1]
	v_pk_fma_f32 v[198:199], v[58:59], v[164:165], v[198:199] op_sel_hi:[1,0,1]
	v_pk_fma_f32 v[200:201], v[60:61], v[164:165], v[200:201] op_sel_hi:[1,0,1]
	v_pk_fma_f32 v[198:199], v[98:99], v[170:171], v[198:199] op_sel_hi:[1,0,1]
	v_pk_fma_f32 v[200:201], v[100:101], v[170:171], v[200:201] op_sel_hi:[1,0,1]
	v_pk_fma_f32 v[198:199], v[62:63], v[176:177], v[198:199] op_sel_hi:[1,0,1]
	v_pk_fma_f32 v[200:201], v[64:65], v[176:177], v[200:201] op_sel_hi:[1,0,1]
	v_pk_fma_f32 v[198:199], v[156:157], v[196:197], v[198:199] op_sel_hi:[1,0,1]
	v_pk_fma_f32 v[200:201], v[158:159], v[196:197], v[200:201] op_sel_hi:[1,0,1]
	v_pk_fma_f32 v[198:199], v[152:153], v[210:211], v[198:199] op_sel_hi:[1,0,1]
	v_pk_fma_f32 v[200:201], v[68:69], v[210:211], v[200:201] op_sel_hi:[1,0,1]
	v_pk_fma_f32 v[198:199], v[166:167], v[218:219], v[198:199] op_sel_hi:[1,0,1]
	v_pk_fma_f32 v[200:201], v[168:169], v[218:219], v[200:201] op_sel_hi:[1,0,1]
	v_pk_fma_f32 v[198:199], v[70:71], v[226:227], v[198:199] op_sel_hi:[1,0,1]
	v_pk_fma_f32 v[200:201], v[72:73], v[226:227], v[200:201] op_sel_hi:[1,0,1]
	v_pk_fma_f32 v[198:199], v[172:173], v[234:235], v[198:199] op_sel_hi:[1,0,1]
	v_pk_fma_f32 v[200:201], v[174:175], v[234:235], v[200:201] op_sel_hi:[1,0,1]
	v_pk_fma_f32 v[234:235], v[88:89], v[104:105], 0 op_sel_hi:[1,0,0]
	v_pk_fma_f32 v[226:227], v[86:87], v[104:105], 0 op_sel_hi:[1,0,0]
	v_pk_fma_f32 v[234:235], v[52:53], v[110:111], v[234:235] op_sel_hi:[1,0,1]
	v_pk_fma_f32 v[226:227], v[84:85], v[110:111], v[226:227] op_sel_hi:[1,0,1]
	v_pk_fma_f32 v[234:235], v[92:93], v[116:117], v[234:235] op_sel_hi:[1,0,1]
	v_pk_fma_f32 v[226:227], v[90:91], v[116:117], v[226:227] op_sel_hi:[1,0,1]
	v_pk_fma_f32 v[234:235], v[56:57], v[124:125], v[234:235] op_sel_hi:[1,0,1]
	v_pk_fma_f32 v[226:227], v[54:55], v[124:125], v[226:227] op_sel_hi:[1,0,1]
	v_pk_fma_f32 v[234:235], v[96:97], v[132:133], v[234:235] op_sel_hi:[1,0,1]
	v_pk_fma_f32 v[226:227], v[94:95], v[132:133], v[226:227] op_sel_hi:[1,0,1]
	v_pk_fma_f32 v[234:235], v[60:61], v[140:141], v[234:235] op_sel_hi:[1,0,1]
	v_pk_fma_f32 v[226:227], v[58:59], v[140:141], v[226:227] op_sel_hi:[1,0,1]
	v_pk_fma_f32 v[234:235], v[100:101], v[148:149], v[234:235] op_sel_hi:[1,0,1]
	v_pk_fma_f32 v[226:227], v[98:99], v[148:149], v[226:227] op_sel_hi:[1,0,1]
	v_pk_fma_f32 v[234:235], v[64:65], v[162:163], v[234:235] op_sel_hi:[1,0,1]
	v_pk_fma_f32 v[226:227], v[62:63], v[162:163], v[226:227] op_sel_hi:[1,0,1]
	v_pk_fma_f32 v[234:235], v[158:159], v[184:185], v[234:235] op_sel_hi:[1,0,1]
	v_pk_fma_f32 v[226:227], v[156:157], v[184:185], v[226:227] op_sel_hi:[1,0,1]
	v_pk_fma_f32 v[234:235], v[68:69], v[190:191], v[234:235] op_sel_hi:[1,0,1]
	v_pk_fma_f32 v[226:227], v[152:153], v[190:191], v[226:227] op_sel_hi:[1,0,1]
	v_pk_fma_f32 v[234:235], v[168:169], v[204:205], v[234:235] op_sel_hi:[1,0,1]
	v_pk_fma_f32 v[226:227], v[166:167], v[204:205], v[226:227] op_sel_hi:[1,0,1]
	v_pk_fma_f32 v[234:235], v[72:73], v[212:213], v[234:235] op_sel_hi:[1,0,1]
	v_pk_fma_f32 v[226:227], v[70:71], v[212:213], v[226:227] op_sel_hi:[1,0,1]
	v_pk_fma_f32 v[234:235], v[174:175], v[220:221], v[234:235] op_sel_hi:[1,0,1]
	v_pk_fma_f32 v[226:227], v[172:173], v[220:221], v[226:227] op_sel_hi:[1,0,1]
	v_pk_fma_f32 v[234:235], v[76:77], v[228:229], v[234:235] op_sel_hi:[1,0,1]
	v_pk_fma_f32 v[226:227], v[74:75], v[228:229], v[226:227] op_sel_hi:[1,0,1]
	v_pk_fma_f32 v[228:229], v[180:181], v[236:237], v[234:235] op_sel_hi:[1,0,1]
	v_pk_fma_f32 v[234:235], v[86:87], v[66:67], 0 op_sel_hi:[1,0,0]
	v_pk_fma_f32 v[66:67], v[88:89], v[66:67], 0 op_sel_hi:[1,0,0]
	v_pk_fma_f32 v[234:235], v[84:85], v[106:107], v[234:235] op_sel_hi:[1,0,1]
	v_pk_fma_f32 v[66:67], v[52:53], v[106:107], v[66:67] op_sel_hi:[1,0,1]
	v_pk_fma_f32 v[234:235], v[90:91], v[112:113], v[234:235] op_sel_hi:[1,0,1]
	v_pk_fma_f32 v[66:67], v[92:93], v[112:113], v[66:67] op_sel_hi:[1,0,1]
	v_pk_fma_f32 v[234:235], v[54:55], v[118:119], v[234:235] op_sel_hi:[1,0,1]
	v_pk_fma_f32 v[66:67], v[56:57], v[118:119], v[66:67] op_sel_hi:[1,0,1]
	v_pk_fma_f32 v[234:235], v[94:95], v[126:127], v[234:235] op_sel_hi:[1,0,1]
	v_pk_fma_f32 v[66:67], v[96:97], v[126:127], v[66:67] op_sel_hi:[1,0,1]
	v_pk_fma_f32 v[234:235], v[58:59], v[134:135], v[234:235] op_sel_hi:[1,0,1]
	v_pk_fma_f32 v[66:67], v[60:61], v[134:135], v[66:67] op_sel_hi:[1,0,1]
	v_pk_fma_f32 v[86:87], v[86:87], v[2:3], 0 op_sel_hi:[1,0,0]
	v_pk_fma_f32 v[88:89], v[88:89], v[2:3], 0 op_sel_hi:[1,0,0]
	v_pk_fma_f32 v[234:235], v[98:99], v[142:143], v[234:235] op_sel_hi:[1,0,1]
	v_pk_fma_f32 v[66:67], v[100:101], v[142:143], v[66:67] op_sel_hi:[1,0,1]
	v_pk_fma_f32 v[52:53], v[52:53], v[102:103], v[88:89] op_sel_hi:[1,0,1]
	v_pk_fma_f32 v[84:85], v[84:85], v[102:103], v[86:87] op_sel_hi:[1,0,1]
	v_pk_fma_f32 v[66:67], v[64:65], v[150:151], v[66:67] op_sel_hi:[1,0,1]
	v_pk_fma_f32 v[234:235], v[62:63], v[150:151], v[234:235] op_sel_hi:[1,0,1]
	v_pk_fma_f32 v[84:85], v[90:91], v[108:109], v[84:85] op_sel_hi:[1,0,1]
	v_pk_fma_f32 v[52:53], v[92:93], v[108:109], v[52:53] op_sel_hi:[1,0,1]
	v_pk_fma_f32 v[234:235], v[156:157], v[160:161], v[234:235] op_sel_hi:[1,0,1]
	v_pk_fma_f32 v[66:67], v[158:159], v[160:161], v[66:67] op_sel_hi:[1,0,1]
	v_pk_fma_f32 v[52:53], v[56:57], v[114:115], v[52:53] op_sel_hi:[1,0,1]
	v_pk_fma_f32 v[54:55], v[54:55], v[114:115], v[84:85] op_sel_hi:[1,0,1]
	v_pk_fma_f32 v[66:67], v[68:69], v[186:187], v[66:67] op_sel_hi:[1,0,1]
	v_pk_fma_f32 v[234:235], v[152:153], v[186:187], v[234:235] op_sel_hi:[1,0,1]
	v_pk_fma_f32 v[54:55], v[94:95], v[122:123], v[54:55] op_sel_hi:[1,0,1]
	v_pk_fma_f32 v[52:53], v[96:97], v[122:123], v[52:53] op_sel_hi:[1,0,1]
	v_pk_fma_f32 v[234:235], v[166:167], v[192:193], v[234:235] op_sel_hi:[1,0,1]
	v_pk_fma_f32 v[66:67], v[168:169], v[192:193], v[66:67] op_sel_hi:[1,0,1]
	v_pk_fma_f32 v[52:53], v[60:61], v[130:131], v[52:53] op_sel_hi:[1,0,1]
	v_pk_fma_f32 v[54:55], v[58:59], v[130:131], v[54:55] op_sel_hi:[1,0,1]
	v_pk_fma_f32 v[66:67], v[72:73], v[206:207], v[66:67] op_sel_hi:[1,0,1]
	v_pk_fma_f32 v[206:207], v[70:71], v[206:207], v[234:235] op_sel_hi:[1,0,1]
	v_pk_fma_f32 v[54:55], v[98:99], v[138:139], v[54:55] op_sel_hi:[1,0,1]
	v_pk_fma_f32 v[52:53], v[100:101], v[138:139], v[52:53] op_sel_hi:[1,0,1]
	v_pk_fma_f32 v[206:207], v[172:173], v[214:215], v[206:207] op_sel_hi:[1,0,1]
	v_pk_fma_f32 v[66:67], v[174:175], v[214:215], v[66:67] op_sel_hi:[1,0,1]
	v_pk_fma_f32 v[52:53], v[64:65], v[146:147], v[52:53] op_sel_hi:[1,0,1]
	v_pk_fma_f32 v[54:55], v[62:63], v[146:147], v[54:55] op_sel_hi:[1,0,1]
	v_pk_fma_f32 v[66:67], v[76:77], v[222:223], v[66:67] op_sel_hi:[1,0,1]
	v_pk_fma_f32 v[206:207], v[74:75], v[222:223], v[206:207] op_sel_hi:[1,0,1]
	v_pk_fma_f32 v[54:55], v[156:157], v[82:83], v[54:55] op_sel_hi:[1,0,1]
	v_pk_fma_f32 v[52:53], v[158:159], v[82:83], v[52:53] op_sel_hi:[1,0,1]
	v_pk_fma_f32 v[206:207], v[178:179], v[230:231], v[206:207] op_sel_hi:[1,0,1]
	v_pk_fma_f32 v[66:67], v[180:181], v[230:231], v[66:67] op_sel_hi:[1,0,1]
	v_pk_fma_f32 v[52:53], v[68:69], v[182:183], v[52:53] op_sel_hi:[1,0,1]
	v_pk_fma_f32 v[54:55], v[152:153], v[182:183], v[54:55] op_sel_hi:[1,0,1]
	v_pk_fma_f32 v[66:67], v[80:81], v[238:239], v[66:67] op_sel_hi:[1,0,1]
	v_pk_fma_f32 v[206:207], v[78:79], v[238:239], v[206:207] op_sel_hi:[1,0,1]
	v_pk_fma_f32 v[54:55], v[166:167], v[188:189], v[54:55] op_sel_hi:[1,0,1]
	v_pk_fma_f32 v[52:53], v[168:169], v[188:189], v[52:53] op_sel_hi:[1,0,1]
	v_pk_fma_f32 v[54:55], v[70:71], v[194:195], v[54:55] op_sel_hi:[1,0,1]
	v_pk_fma_f32 v[52:53], v[72:73], v[194:195], v[52:53] op_sel_hi:[1,0,1]
	ds_bpermute_b32 v56, v149, v206
	ds_bpermute_b32 v57, v149, v207
	ds_bpermute_b32 v58, v149, v66
	ds_bpermute_b32 v59, v149, v67
	v_pk_fma_f32 v[54:55], v[172:173], v[208:209], v[54:55] op_sel_hi:[1,0,1]
	v_pk_fma_f32 v[52:53], v[174:175], v[208:209], v[52:53] op_sel_hi:[1,0,1]
	v_pk_fma_f32 v[200:201], v[76:77], v[240:241], v[200:201] op_sel_hi:[1,0,1]
	v_pk_fma_f32 v[198:199], v[74:75], v[240:241], v[198:199] op_sel_hi:[1,0,1]
	v_pk_fma_f32 v[52:53], v[76:77], v[216:217], v[52:53] op_sel_hi:[1,0,1]
	v_pk_fma_f32 v[54:55], v[74:75], v[216:217], v[54:55] op_sel_hi:[1,0,1]
	v_pk_fma_f32 v[198:199], v[178:179], v[244:245], v[198:199] op_sel_hi:[1,0,1]
	v_pk_fma_f32 v[200:201], v[180:181], v[244:245], v[200:201] op_sel_hi:[1,0,1]
	v_pk_fma_f32 v[226:227], v[178:179], v[236:237], v[226:227] op_sel_hi:[1,0,1]
	v_pk_fma_f32 v[54:55], v[178:179], v[224:225], v[54:55] op_sel_hi:[1,0,1]
	v_pk_fma_f32 v[52:53], v[180:181], v[224:225], v[52:53] op_sel_hi:[1,0,1]
	v_pk_fma_f32 v[200:201], v[80:81], v[246:247], v[200:201] op_sel_hi:[1,0,1]
	v_pk_fma_f32 v[198:199], v[78:79], v[246:247], v[198:199] op_sel_hi:[1,0,1]
	v_pk_fma_f32 v[228:229], v[80:81], v[242:243], v[228:229] op_sel_hi:[1,0,1]
	v_pk_fma_f32 v[226:227], v[78:79], v[242:243], v[226:227] op_sel_hi:[1,0,1]
	v_pk_fma_f32 v[80:81], v[80:81], v[232:233], v[52:53] op_sel_hi:[1,0,1]
	v_pk_fma_f32 v[74:75], v[78:79], v[232:233], v[54:55] op_sel_hi:[1,0,1]
	s_waitcnt lgkmcnt(2)
	v_pk_add_f32 v[52:53], v[206:207], v[56:57]
	s_waitcnt lgkmcnt(0)
	v_pk_add_f32 v[56:57], v[66:67], v[58:59]
	ds_bpermute_b32 v58, v149, v226
	ds_bpermute_b32 v59, v149, v227
	ds_bpermute_b32 v64, v149, v228
	ds_bpermute_b32 v65, v149, v229
	ds_bpermute_b32 v66, v149, v198
	ds_bpermute_b32 v67, v149, v199
	ds_bpermute_b32 v72, v149, v200
	ds_bpermute_b32 v73, v149, v201
	ds_bpermute_b32 v76, v149, v74
	ds_bpermute_b32 v77, v149, v75
	ds_bpermute_b32 v82, v149, v80
	ds_bpermute_b32 v83, v149, v81
	s_waitcnt lgkmcnt(10)
	v_pk_add_f32 v[58:59], v[226:227], v[58:59]
	s_waitcnt lgkmcnt(8)
	v_pk_add_f32 v[64:65], v[228:229], v[64:65]
	s_waitcnt lgkmcnt(6)
	v_pk_add_f32 v[66:67], v[198:199], v[66:67]
	s_waitcnt lgkmcnt(4)
	v_pk_add_f32 v[72:73], v[200:201], v[72:73]
	s_waitcnt lgkmcnt(2)
	v_pk_add_f32 v[74:75], v[74:75], v[76:77]
	s_waitcnt lgkmcnt(0)
	v_pk_add_f32 v[80:81], v[80:81], v[82:83]
	ds_bpermute_b32 v54, v151, v52
	ds_bpermute_b32 v55, v151, v53
	ds_bpermute_b32 v62, v151, v56
	ds_bpermute_b32 v63, v151, v57
	ds_bpermute_b32 v60, v151, v58
	ds_bpermute_b32 v61, v151, v59
	ds_bpermute_b32 v70, v151, v64
	ds_bpermute_b32 v71, v151, v65
	ds_bpermute_b32 v68, v151, v66
	ds_bpermute_b32 v69, v151, v67
	ds_bpermute_b32 v78, v151, v72
	ds_bpermute_b32 v79, v151, v73
	ds_bpermute_b32 v76, v151, v74
	ds_bpermute_b32 v77, v151, v75
	ds_bpermute_b32 v82, v151, v80
	ds_bpermute_b32 v83, v151, v81
	v_lshlrev_b32_e32 v2, 10, v1
	v_lshlrev_b32_e32 v84, 4, v107
	v_cmp_gt_u32_e64 s[46:47], 16, v107
	v_add3_u32 v101, 0, v2, v84
	s_and_saveexec_b64 s[2:3], s[46:47]
	s_cbranch_execz .LBB0_1742
	s_waitcnt lgkmcnt(12)
	v_pk_add_f32 v[56:57], v[56:57], v[62:63]
	v_pk_add_f32 v[54:55], v[52:53], v[54:55]
	ds_write_b128 v101, v[54:57] offset:19584
	s_waitcnt lgkmcnt(9)
	v_pk_add_f32 v[54:55], v[64:65], v[70:71]
	v_pk_add_f32 v[52:53], v[58:59], v[60:61]
	ds_write_b128 v101, v[52:55] offset:19840
	s_waitcnt lgkmcnt(6)
	v_pk_add_f32 v[54:55], v[72:73], v[78:79]
	v_pk_add_f32 v[52:53], v[66:67], v[68:69]
	ds_write_b128 v101, v[52:55] offset:20096
	s_waitcnt lgkmcnt(3)
	v_pk_add_f32 v[54:55], v[80:81], v[82:83]
	v_pk_add_f32 v[52:53], v[74:75], v[76:77]
	ds_write_b128 v101, v[52:55] offset:20352

.LBB0_2362:
	v_mov_b32_e32 v248, 0x41a00000
	v_mov_b32_e32 v249, 0x35800000
	v_mov_b64_e32 v[202:203], 0x100
	v_mov_b64_e32 v[250:251], 0xff
	s_setprio 0
	v_readlane_b32 s0, v255, 40
	s_add_i32 s44, s0, 1
	v_readlane_b32 s0, v253, 5
	v_readlane_b32 s1, v253, 6
	s_cmp_lt_i32 s44, s1
	v_readlane_b32 s2, v255, 28
	s_cselect_b64 s[0:1], -1, 0
	v_readlane_b32 s3, v255, 29
	s_and_b64 s[0:1], s[2:3], s[0:1]
	s_and_b64 vcc, exec, s[0:1]
	v_readlane_b32 s64, v255, 32
	s_cbranch_vccz .LBB0_2412
	s_waitcnt vmcnt(0)
	s_waitcnt vmcnt(0)
	s_barrier
	s_mov_b64 s[2:3], exec
	v_readlane_b32 s0, v253, 2
	v_readlane_b32 s1, v253, 3
	s_and_b64 s[0:1], s[2:3], s[0:1]
	s_mov_b64 exec, s[0:1]
	s_cbranch_execz .LBB0_2411
	v_readlane_b32 s0, v253, 1
	s_waitcnt vmcnt(0) expcnt(0) lgkmcnt(0)
	s_nop 0
	v_mov_b32_e32 v1, s0
	ds_read_b32 v4, v1
	ds_read_b32 v2, v1 offset:4
	s_waitcnt lgkmcnt(1)
	v_cmp_ne_u32_e32 vcc, 0, v4
	s_cbranch_vccnz .LBB0_2379
	v_readlane_b32 s4, v253, 7
	v_readlane_b32 s5, v253, 8
	s_load_dwordx2 s[0:1], s[4:5], 0x0
	s_nop 0
	s_load_dword s4, s[4:5], 0x8
	s_waitcnt lgkmcnt(0)
	s_mul_i32 s0, s1, s0
	s_mul_i32 s0, s0, s4
	s_mov_b32 s1, 1
	s_branch .LBB0_2367
